# selected-branch block loop: wave-level any-masks precomputed once per unit (scalar skip test), lane masks computed in the shadow of the K-fragment loads
# baseline (speedup 1.0000x reference)
; template <bool SEL> ...
;     ...
;             if (SEL) {
; #pragma unroll
;                 for (int cg_ = 0; cg_ < 2; ++cg_) {
;                     const unsigned long long wsel = j < 64 ? sw[cg_][0] : sw[cg_][1];
;                     selq[cg_] = ((wsel >> (j & 63)) & 1ull) != 0ull; any[cg_] = __any(selq[cg_]) != 0;
;                 }
; __device__ __forceinline__ void unitA(unsigned char* lds, PG8_LAS unsigned char* lds3, const Args& a, int b, int g, int T) {
;     ...
;     unsigned long long sw[2][2];
; #pragma unroll
;     for (int cg_ = 0; cg_ < 2; ++cg_) { const unsigned* sp = selm + (8 * w + 4 * cg_ + (c >> 2)) * 4;
;         sw[cg_][0] = (unsigned long long)sp[0] | ((unsigned long long)sp[1] << 32); sw[cg_][1] = (unsigned long long)sp[2] | ((unsigned long long)sp[3] << 32); }
.LBB0_2468:
	v_and_b32_e32 v19, 1, v133
	v_cmp_eq_u32_e32 vcc, 0, v19
	s_nop 0
	v_mov_b32_dpp v19, v52 quad_perm:[1,0,3,2] row_mask:0xf bank_mask:0xf bound_ctrl:1
	s_and_saveexec_b64 s[8:9], vcc
	v_lshlrev_b32_e32 v53, 4, v145
	v_lshlrev_b32_e32 v54, 1, v146
	v_add3_u32 v53, s86, v53, v54
	v_lshl_or_b32 v19, v19, 16, v52
	ds_write_b32 v53, v19
	s_or_b64 exec, exec, s[8:9]
	v_mul_f32_e32 v19, 0xbfb8aa3b, v144
	v_exp_f32_e32 v19, v19
	s_waitcnt lgkmcnt(0)
	s_barrier
	v_add_f32_e32 v19, 1.0, v19
	v_rcp_f32_e32 v52, v19
	v_lshl_add_u32 v19, v133, 4, 0
	v_add_u32_e32 v178, 0x12500, v19
	s_lshl_b32 s42, s36, 21
	v_pk_mul_f32 v[38:39], v[52:53], v[38:39] op_sel_hi:[0,1]
	v_pk_mul_f32 v[36:37], v[52:53], v[36:37] op_sel_hi:[0,1]
	ds_write_b128 v178, v[36:39]
	v_pk_mul_f32 v[38:39], v[52:53], v[50:51] op_sel_hi:[0,1]
	v_pk_mul_f32 v[36:37], v[52:53], v[48:49] op_sel_hi:[0,1]
	ds_write_b128 v178, v[36:39] offset:8192
	v_mul_f32_e32 v36, 0xbfb8aa3b, v143
	v_exp_f32_e32 v36, v36
	v_pk_mul_f32 v[34:35], v[52:53], v[34:35] op_sel_hi:[0,1]
	v_pk_mul_f32 v[32:33], v[52:53], v[32:33] op_sel_hi:[0,1]
	ds_write_b128 v178, v[32:35] offset:16384
	v_add_f32_e32 v32, 1.0, v36
	v_rcp_f32_e32 v36, v32
	v_pk_mul_f32 v[34:35], v[52:53], v[42:43] op_sel_hi:[0,1]
	v_pk_mul_f32 v[32:33], v[52:53], v[40:41] op_sel_hi:[0,1]
	ds_write_b128 v178, v[32:35] offset:24576
	v_pk_mul_f32 v[22:23], v[36:37], v[22:23] op_sel_hi:[0,1]
	v_pk_mul_f32 v[20:21], v[36:37], v[20:21] op_sel_hi:[0,1]
	v_pk_mul_f32 v[26:27], v[36:37], v[26:27] op_sel_hi:[0,1]
	v_pk_mul_f32 v[24:25], v[36:37], v[24:25] op_sel_hi:[0,1]
	ds_write_b128 v178, v[20:23] offset:57344
	v_and_b32_e32 v20, 12, v133
	v_pk_mul_f32 v[30:31], v[36:37], v[30:31] op_sel_hi:[0,1]
	v_pk_mul_f32 v[28:29], v[36:37], v[28:29] op_sel_hi:[0,1]
	ds_write_b128 v178, v[24:27] offset:40960
	v_pk_mul_f32 v[26:27], v[36:37], v[46:47] op_sel_hi:[0,1]
	v_pk_mul_f32 v[24:25], v[36:37], v[44:45] op_sel_hi:[0,1]
	v_lshlrev_b32_e32 v21, 7, v141
	v_lshlrev_b32_e32 v20, 2, v20
	ds_write_b128 v178, v[28:31] offset:32768
	ds_write_b128 v178, v[24:27] offset:49152
	v_add3_u32 v20, s86, v21, v20
	ds_read_b128 v[32:35], v20
	ds_read_b128 v[36:39], v20 offset:64
	s_cmp_gt_i32 s0, -1
	s_cselect_b64 s[28:29], -1, 0
	s_add_u32 s43, s67, s42
	s_addc_u32 s44, s72, 0
	s_waitcnt lgkmcnt(0)
	v_readlane_b32 s36, v32, 0
	v_readlane_b32 s6, v32, 4
	s_or_b32 s36, s36, s6
	v_readlane_b32 s6, v32, 8
	s_or_b32 s36, s36, s6
	v_readlane_b32 s6, v32, 12
	s_or_b32 s36, s36, s6
	v_readlane_b32 s6, v36, 0
	s_or_b32 s36, s36, s6
	v_readlane_b32 s6, v36, 4
	s_or_b32 s36, s36, s6
	v_readlane_b32 s6, v36, 8
	s_or_b32 s36, s36, s6
	v_readlane_b32 s6, v36, 12
	s_or_b32 s36, s36, s6
	v_readlane_b32 s37, v33, 0
	v_readlane_b32 s6, v33, 4
	s_or_b32 s37, s37, s6
	v_readlane_b32 s6, v33, 8
	s_or_b32 s37, s37, s6
	v_readlane_b32 s6, v33, 12
	s_or_b32 s37, s37, s6
	v_readlane_b32 s6, v37, 0
	s_or_b32 s37, s37, s6
	v_readlane_b32 s6, v37, 4
	s_or_b32 s37, s37, s6
	v_readlane_b32 s6, v37, 8
	s_or_b32 s37, s37, s6
	v_readlane_b32 s6, v37, 12
	s_or_b32 s37, s37, s6
	v_readlane_b32 s38, v34, 0
	v_readlane_b32 s6, v34, 4
	s_or_b32 s38, s38, s6
	v_readlane_b32 s6, v34, 8
	s_or_b32 s38, s38, s6
	v_readlane_b32 s6, v34, 12
	s_or_b32 s38, s38, s6
	v_readlane_b32 s6, v38, 0
	s_or_b32 s38, s38, s6
	v_readlane_b32 s6, v38, 4
	s_or_b32 s38, s38, s6
	v_readlane_b32 s6, v38, 8
	s_or_b32 s38, s38, s6
	v_readlane_b32 s6, v38, 12
	s_or_b32 s38, s38, s6
	v_readlane_b32 s39, v35, 0
	v_readlane_b32 s6, v35, 4
	s_or_b32 s39, s39, s6
	v_readlane_b32 s6, v35, 8
	s_or_b32 s39, s39, s6
	v_readlane_b32 s6, v35, 12
	s_or_b32 s39, s39, s6
	v_readlane_b32 s6, v39, 0
	s_or_b32 s39, s39, s6
	v_readlane_b32 s6, v39, 4
	s_or_b32 s39, s39, s6
	v_readlane_b32 s6, v39, 8
	s_or_b32 s39, s39, s6
	v_readlane_b32 s6, v39, 12
	s_or_b32 s39, s39, s6
	s_cmp_lt_i32 s0, 0
	s_waitcnt lgkmcnt(0)
	s_barrier
	s_cbranch_scc1 .LBB0_2645
	s_mov_b32 s1, s5
	s_lshl_b64 s[6:7], s[0:1], 14
	s_add_u32 s6, s43, s6
	s_addc_u32 s7, s44, s7
	v_lshl_add_u64 v[20:21], s[6:7], 0, v[0:1]
	s_mov_b32 s1, m0
	s_mov_b32 m0, s95
	s_nop 0
	global_load_lds_dwordx4 v[20:21], off
	s_mov_b32 m0, s1
	v_lshl_add_u64 v[22:23], v[20:21], 0, s[62:63]
	s_add_i32 s1, s95, 0x2000
	s_mov_b32 s4, m0
	s_mov_b32 m0, s1
	s_nop 0
	global_load_lds_dwordx4 v[22:23], off
	s_mov_b32 m0, s4
	s_cmp_gt_i32 s0, 0
	s_cselect_b64 s[30:31], -1, 0
	s_cmp_lt_i32 s0, 1
	s_cbranch_scc0 .LBB0_2646

; template <bool SEL> ...
;     ...
;         for (int it = it0; it < it0 + 2 && it < n; ++it) {
;             const int j = jhi - it, slot = it & 3;
;             bool selq[2] = {true, true}; bool any[2] = {true, true};
;             if (SEL) {
; #pragma unroll
;                 for (int cg_ = 0; cg_ < 2; ++cg_) {
;                     const unsigned long long wsel = j < 64 ? sw[cg_][0] : sw[cg_][1];
;                     selq[cg_] = ((wsel >> (j & 63)) & 1ull) != 0ull; any[cg_] = __any(selq[cg_]) != 0;
;                 }
;             }
;             if (any[0] || any[1]) {
;                 const unsigned char* Ks = lds + OFF_RING + slot * SLOTB; const unsigned char* Vs = Ks + 8192;
;                 bf16x8 kf[4][2]; load_kfrags(kf, Ks, r, fq);
;                 const bool edge = (j >= T - 2) || (wl == 512 && j == T - 8);
;                 if (edge) {
.LBB0_2482:
	s_cmp_lt_i32 s48, 64
	s_cselect_b64 s[6:7], s[36:37], s[38:39]
	s_bitcmp1_b64 s[6:7], s48
	s_cbranch_scc0 .LBB0_2481
	s_and_b32 s6, s49, 0xc000
	v_add_u32_e32 v60, s6, v140
	v_add_u32_e32 v143, v60, v136
	v_add_u32_e32 v142, v60, v137
	ds_read_b128 v[88:91], v143
	ds_read_b128 v[80:83], v143 offset:512
	ds_read_b128 v[84:87], v142
	ds_read_b128 v[76:79], v142 offset:512
	ds_read_b128 v[72:75], v143 offset:4096
	ds_read_b128 v[60:63], v143 offset:4608
	ds_read_b128 v[68:71], v142 offset:4096
	ds_read_b128 v[64:67], v142 offset:4608
	s_cmp_lt_i32 s48, 64
	s_cselect_b64 vcc, -1, 0
	s_lshl_b64 s[6:7], 1, s48
	v_cndmask_b32_e32 v249, v35, v33, vcc
	v_cndmask_b32_e32 v248, v34, v32, vcc
	v_cndmask_b32_e32 v251, v39, v37, vcc
	v_cndmask_b32_e32 v250, v38, v36, vcc
	v_and_b32_e32 v249, s7, v249
	v_and_b32_e32 v248, s6, v248
	v_and_b32_e32 v251, s7, v251
	v_and_b32_e32 v250, s6, v250
	v_cmp_ne_u64_e64 s[10:11], 0, v[248:249]
	v_cmp_ne_u64_e64 s[8:9], 0, v[250:251]
	s_cmp_lt_i32 s48, s93
	s_cbranch_scc1 .Lsel_int
	s_branch .Lsel_edge
	s_and_b64 vcc, exec, s[38:39]
	s_cbranch_vccz .LBB0_2557
	s_and_b64 vcc, exec, s[36:37]
	s_cbranch_vccz .LBB0_2521
	s_waitcnt lgkmcnt(7)
	v_mfma_f32_16x16x32_bf16 v[92:95], v[88:91], v[10:13], 0
	v_add_u32_e32 v119, s4, v141
	v_add_u32_e32 v110, 4, v119
	v_cmp_gt_u32_e32 vcc, 2.0, v110
	s_waitcnt lgkmcnt(5)
	v_mfma_f32_16x16x32_bf16 v[104:107], v[84:87], v[14:17], v[92:95]
	v_mov_b32_e32 v108, 0xf149f2ca
	v_mov_b32_e32 v109, 0xf149f2ca
	v_mfma_f32_16x16x32_bf16 v[92:95], v[80:83], v[10:13], 0
	s_waitcnt lgkmcnt(4)
	v_mfma_f32_16x16x32_bf16 v[100:103], v[76:79], v[14:17], v[92:95]
	s_waitcnt lgkmcnt(3)
	v_mfma_f32_16x16x32_bf16 v[92:95], v[72:75], v[10:13], 0
	s_waitcnt lgkmcnt(1)
	v_mfma_f32_16x16x32_bf16 v[96:99], v[68:71], v[14:17], v[92:95]
	v_mfma_f32_16x16x32_bf16 v[92:95], v[60:63], v[10:13], 0
	s_waitcnt lgkmcnt(0)
	v_mfma_f32_16x16x32_bf16 v[92:95], v[64:67], v[14:17], v[92:95]
	s_and_saveexec_b64 s[12:13], vcc
	s_cbranch_execz .LBB0_2488
	v_min_u32_e32 v109, 0x80, v110
	v_lshl_add_u32 v109, v109, 6, v177
	ds_read_b32 v109, v109
	s_waitcnt lgkmcnt(0)
	v_add_f32_e32 v109, v104, v109
